# SGPR-base LDS-DMA addressing also in the peeled first K-iterations (92 address VALU ops removed in total); snake MFMA order
# baseline (speedup 1.0000x reference)
; template <class Epi, class Sched, bool ALIGN_EPI = false, bool SP2 = false>
; __device__ __forceinline__ void gemm_phase(PG8_LAS unsigned char* lds, const Gemm g, const Sched& S, const Epi& E) {
;     ...
;         if constexpr (Epi::PEEL) {
;             const char* a1 = cA + kstepA; const char* a2 = cA + 2 * kstepA; const char* b2 = cB + 2 * kstepB; const char* a3 = a2 + kstepA; const char* b3 = b2 + kstepB;
;             PG8_ITER(8);
;         }
.LBB0_160:
	s_ashr_i32 s55, s54, 31
	s_lshl_b64 s[2:3], s[54:55], 15
	v_readlane_b32 s8, v255, 15
	s_add_u32 s12, s8, s2
	v_readlane_b32 s2, v255, 16
	s_addc_u32 s13, s2, s3
	s_ashr_i32 s49, s48, 31
	s_lshl_b64 s[2:3], s[48:49], 19
	v_readlane_b32 s8, v255, 29
	s_add_u32 s46, s8, s2
	v_readlane_b32 s2, v255, 40
	s_addc_u32 s47, s2, s3
	s_add_u32 s28, s24, 0x800000
	s_addc_u32 s29, s25, 0
	s_add_u32 s42, s24, 0xc00000
	s_addc_u32 s43, s25, 0
	s_add_i32 s55, 0, 0x10000
	s_and_b64 s[2:3], s[30:31], exec
	s_cselect_b32 s27, s13, s25
	s_cselect_b32 s44, s12, s24
	s_add_i32 vcc_hi, 0, 0x14000
	v_add_u32_e32 v142, s55, v97
	v_add_u32_e32 v143, vcc_hi, v97
	ds_read_b128 v[0:3], v142
	ds_read_b128 v[4:7], v142 offset:1024
	ds_read_b128 v[8:11], v142 offset:2048
	ds_read_b128 v[12:15], v142 offset:3072
	ds_read_b128 v[16:19], v143
	s_waitcnt lgkmcnt(0)
	ds_read_b128 v[20:23], v143 offset:1024
	ds_read_b128 v[24:27], v143 offset:2048
	ds_read_b128 v[28:31], v143 offset:3072
	v_writelane_b32 v255, s30, 33
	s_and_b64 s[2:3], s[30:31], exec
	s_cselect_b32 s45, s47, s1
	v_writelane_b32 v255, s31, 34
	s_cselect_b32 s49, s46, s0
	s_add_u32 s2, s24, 0x404000
	s_addc_u32 s3, s25, 0
	s_add_i32 s50, s22, 0xc000
	s_mov_b32 m0, s50
	s_add_i32 s51, s22, 0xe000
	ds_read_b128 v[32:35], v161
	ds_read_b128 v[36:39], v161 offset:1024
	ds_read_b128 v[40:43], v161 offset:2048
	ds_read_b128 v[44:47], v161 offset:3072
	ds_read_b128 v[48:51], v161 offset:4096
	ds_read_b128 v[52:55], v161 offset:5120
	ds_read_b128 v[56:59], v161 offset:6144
	ds_read_b128 v[60:63], v161 offset:7168
	global_load_lds_dwordx4 v130, s[2:3]
	s_mov_b32 m0, s51
	s_nop 0
	global_load_lds_dwordx4 v134, s[2:3]
	s_waitcnt vmcnt(8)
	s_waitcnt lgkmcnt(0)
	s_barrier
	s_setprio 1
	s_waitcnt lgkmcnt(0)
	v_mfma_f32_16x16x32_bf16 v[64:67], v[0:3], v[32:35], 0
	v_mfma_f32_16x16x32_bf16 v[68:71], v[8:11], v[32:35], 0
	v_mfma_f32_16x16x32_bf16 v[72:75], v[0:3], v[40:43], 0
	v_mfma_f32_16x16x32_bf16 v[76:79], v[8:11], v[40:43], 0
	v_mfma_f32_16x16x32_bf16 v[80:83], v[0:3], v[48:51], 0
	v_mfma_f32_16x16x32_bf16 v[84:87], v[8:11], v[48:51], 0
	v_mfma_f32_16x16x32_bf16 v[88:91], v[0:3], v[56:59], 0
	v_mfma_f32_16x16x32_bf16 v[92:95], v[8:11], v[56:59], 0
	v_mfma_f32_16x16x32_bf16 v[64:67], v[4:7], v[36:39], v[64:67]
	v_mfma_f32_16x16x32_bf16 v[68:71], v[12:15], v[36:39], v[68:71]
	v_mfma_f32_16x16x32_bf16 v[72:75], v[4:7], v[44:47], v[72:75]
	v_mfma_f32_16x16x32_bf16 v[76:79], v[12:15], v[44:47], v[76:79]
	v_mfma_f32_16x16x32_bf16 v[80:83], v[4:7], v[52:55], v[80:83]
	v_mfma_f32_16x16x32_bf16 v[84:87], v[12:15], v[52:55], v[84:87]
	v_mfma_f32_16x16x32_bf16 v[88:91], v[4:7], v[60:63], v[88:91]
	v_mfma_f32_16x16x32_bf16 v[98:101], v[12:15], v[60:63], v[92:95]
	s_setprio 0
	s_setprio 1
	v_mfma_f32_16x16x32_bf16 v[92:95], v[16:19], v[32:35], 0
	v_mfma_f32_16x16x32_bf16 v[32:35], v[24:27], v[32:35], 0
	v_mfma_f32_16x16x32_bf16 v[106:109], v[20:23], v[36:39], v[92:95]
	v_mfma_f32_16x16x32_bf16 v[32:35], v[28:31], v[36:39], v[32:35]
	v_mfma_f32_16x16x32_bf16 v[36:39], v[16:19], v[40:43], 0
	v_mfma_f32_16x16x32_bf16 v[40:43], v[24:27], v[40:43], 0
	v_mfma_f32_16x16x32_bf16 v[36:39], v[20:23], v[44:47], v[36:39]
	v_mfma_f32_16x16x32_bf16 v[40:43], v[28:31], v[44:47], v[40:43]
	v_mfma_f32_16x16x32_bf16 v[44:47], v[16:19], v[48:51], 0
	v_mfma_f32_16x16x32_bf16 v[48:51], v[24:27], v[48:51], 0
	v_mfma_f32_16x16x32_bf16 v[44:47], v[20:23], v[52:55], v[44:47]
	v_mfma_f32_16x16x32_bf16 v[48:51], v[28:31], v[52:55], v[48:51]
	v_mfma_f32_16x16x32_bf16 v[52:55], v[16:19], v[56:59], 0
	v_mfma_f32_16x16x32_bf16 v[56:59], v[24:27], v[56:59], 0
	v_mfma_f32_16x16x32_bf16 v[52:55], v[20:23], v[60:63], v[52:55]
	v_mfma_f32_16x16x32_bf16 v[56:59], v[28:31], v[60:63], v[56:59]
	s_setprio 0
	s_barrier
	v_lshl_add_u64 v[158:159], s[0:1], 0, v[132:133]
	s_mov_b64 s[2:3], 0x100
	s_add_i32 s55, s55, s10
	v_lshl_add_u64 v[144:145], v[158:159], 0, s[2:3]
	s_mov_b32 m0, s55
	v_lshl_add_u64 v[178:179], s[0:1], 0, v[136:137]
	s_add_i32 vcc_lo, s55, 0x2000
	ds_read_b128 v[60:63], v161 offset:16384
	ds_read_b128 v[92:95], v161 offset:17408
	ds_read_b128 v[102:105], v161 offset:18432
	ds_read_b128 v[110:113], v161 offset:19456
	ds_read_b128 v[114:117], v161 offset:20480
	ds_read_b128 v[118:121], v161 offset:21504
	ds_read_b128 v[122:125], v161 offset:22528
	ds_read_b128 v[126:129], v161 offset:23552
	global_load_lds_dwordx4 v[144:145], off
	v_lshl_add_u64 v[144:145], v[178:179], 0, s[2:3]
	s_add_u32 s2, s0, 0x40100
	s_mov_b32 m0, vcc_lo
	s_addc_u32 s3, s1, 0
	s_add_i32 vcc_hi, vcc_hi, s10
	global_load_lds_dwordx4 v[144:145], off
	s_mov_b32 m0, vcc_hi
	s_add_i32 s56, vcc_hi, 0x2000
	global_load_lds_dwordx4 v132, s[2:3]
	s_mov_b32 m0, s56
	s_nop 0
	global_load_lds_dwordx4 v136, s[2:3]
	s_mov_b32 m0, s22
	s_nop 0
	global_load_lds_dwordx4 v130, s[28:29]
	s_mov_b32 m0, s23
	s_nop 0
	global_load_lds_dwordx4 v134, s[28:29]
	s_waitcnt vmcnt(8)
	s_waitcnt lgkmcnt(0)
	s_barrier
; template <class Epi, class Sched, bool ALIGN_EPI = false, bool SP2 = false>
; __device__ __forceinline__ void gemm_phase(PG8_LAS unsigned char* lds, const Gemm g, const Sched& S, const Epi& E) {
;     ...
;         if constexpr (Epi::PEEL) {
;             const char* a1 = cA + kstepA; const char* a2 = cA + 2 * kstepA; const char* b2 = cB + 2 * kstepB; const char* a3 = a2 + kstepA; const char* b3 = b2 + kstepB;
;             PG8_ITER(8);
;         }
	s_setprio 1
	s_waitcnt lgkmcnt(0)
	v_mfma_f32_16x16x32_bf16 v[144:147], v[0:3], v[60:63], 0
	v_mfma_f32_16x16x32_bf16 v[154:157], v[0:3], v[102:105], 0
	v_mfma_f32_16x16x32_bf16 v[166:169], v[0:3], v[114:117], 0
	v_mfma_f32_16x16x32_bf16 v[0:3], v[0:3], v[122:125], 0
	v_mfma_f32_16x16x32_bf16 v[146:149], v[4:7], v[92:95], v[144:147]
	v_mfma_f32_16x16x32_bf16 v[154:157], v[4:7], v[110:113], v[154:157]
	v_mfma_f32_16x16x32_bf16 v[166:169], v[4:7], v[118:121], v[166:169]
	v_mfma_f32_16x16x32_bf16 v[0:3], v[4:7], v[126:129], v[0:3]
	v_mfma_f32_16x16x32_bf16 v[4:7], v[8:11], v[122:125], 0
	v_mfma_f32_16x16x32_bf16 v[150:153], v[8:11], v[60:63], 0
	v_mfma_f32_16x16x32_bf16 v[162:165], v[8:11], v[102:105], 0
	v_mfma_f32_16x16x32_bf16 v[170:173], v[8:11], v[114:117], 0
	v_mfma_f32_16x16x32_bf16 v[4:7], v[12:15], v[126:129], v[4:7]
	v_mfma_f32_16x16x32_bf16 v[150:153], v[12:15], v[92:95], v[150:153]
	v_mfma_f32_16x16x32_bf16 v[162:165], v[12:15], v[110:113], v[162:165]
	v_mfma_f32_16x16x32_bf16 v[170:173], v[12:15], v[118:121], v[170:173]
	s_setprio 0
	s_setprio 1
	v_mfma_f32_16x16x32_bf16 v[12:15], v[24:27], v[60:63], 0
	v_mfma_f32_16x16x32_bf16 v[174:177], v[28:31], v[92:95], v[12:15]
	v_mfma_f32_16x16x32_bf16 v[12:15], v[16:19], v[102:105], 0
	v_mfma_f32_16x16x32_bf16 v[180:183], v[20:23], v[110:113], v[12:15]
	v_mfma_f32_16x16x32_bf16 v[12:15], v[24:27], v[102:105], 0
	v_mfma_f32_16x16x32_bf16 v[184:187], v[28:31], v[110:113], v[12:15]
	v_mfma_f32_16x16x32_bf16 v[12:15], v[16:19], v[114:117], 0
	v_mfma_f32_16x16x32_bf16 v[188:191], v[20:23], v[118:121], v[12:15]
	v_mfma_f32_16x16x32_bf16 v[12:15], v[24:27], v[114:117], 0
	v_mfma_f32_16x16x32_bf16 v[8:11], v[16:19], v[60:63], 0
	v_mfma_f32_16x16x32_bf16 v[192:195], v[28:31], v[118:121], v[12:15]
	v_mfma_f32_16x16x32_bf16 v[12:15], v[16:19], v[122:125], 0
	v_mfma_f32_16x16x32_bf16 v[8:11], v[20:23], v[92:95], v[8:11]
	v_mfma_f32_16x16x32_bf16 v[196:199], v[20:23], v[126:129], v[12:15]
	v_mfma_f32_16x16x32_bf16 v[12:15], v[24:27], v[122:125], 0
	v_mfma_f32_16x16x32_bf16 v[200:203], v[28:31], v[126:129], v[12:15]
	s_setprio 0
	s_barrier
	s_add_i32 s30, 0, 0x18000
	s_add_i32 s57, 0, 0x1c000
	v_add_u32_e32 v144, s30, v97
	v_add_u32_e32 v145, s57, v97
	s_nop 0
	ds_read_b128 v[12:15], v144
	ds_read_b128 v[16:19], v144 offset:1024
	ds_read_b128 v[24:27], v144 offset:2048
	ds_read_b128 v[204:207], v144 offset:3072
	ds_read_b128 v[208:211], v145
	ds_read_b128 v[212:215], v145 offset:1024
	ds_read_b128 v[216:219], v145 offset:2048
	ds_read_b128 v[220:223], v145 offset:3072
	s_add_u32 s2, s24, 0x804000
	s_addc_u32 s3, s25, 0
	s_mov_b32 m0, s39
	ds_read_b128 v[20:23], v161 offset:32768
	ds_read_b128 v[28:31], v161 offset:33792
	ds_read_b128 v[60:63], v161 offset:34816
	ds_read_b128 v[224:227], v161 offset:35840
	ds_read_b128 v[228:231], v161 offset:36864
	ds_read_b128 v[234:237], v161 offset:37888
	ds_read_b128 v[238:241], v161 offset:38912
	ds_read_b128 v[242:245], v161 offset:39936
	global_load_lds_dwordx4 v130, s[2:3]
	s_mov_b32 m0, s52
	s_nop 0
	global_load_lds_dwordx4 v134, s[2:3]
	s_waitcnt vmcnt(8)
	s_waitcnt lgkmcnt(0)
	s_barrier
	s_setprio 1
	s_waitcnt lgkmcnt(0)
	v_mfma_f32_16x16x32_bf16 v[64:67], v[12:15], v[20:23], v[64:67]
	v_mfma_f32_16x16x32_bf16 v[126:129], v[16:19], v[28:31], v[64:67]
	v_mfma_f32_16x16x32_bf16 v[64:67], v[24:27], v[20:23], v[68:71]
	v_mfma_f32_16x16x32_bf16 v[118:121], v[204:207], v[28:31], v[64:67]
	v_mfma_f32_16x16x32_bf16 v[64:67], v[12:15], v[60:63], v[72:75]
	v_mfma_f32_16x16x32_bf16 v[110:113], v[16:19], v[224:227], v[64:67]
	v_mfma_f32_16x16x32_bf16 v[64:67], v[24:27], v[60:63], v[76:79]
	v_mfma_f32_16x16x32_bf16 v[102:105], v[204:207], v[224:227], v[64:67]
	v_mfma_f32_16x16x32_bf16 v[64:67], v[12:15], v[228:231], v[80:83]
	v_mfma_f32_16x16x32_bf16 v[92:95], v[16:19], v[234:237], v[64:67]
	v_mfma_f32_16x16x32_bf16 v[64:67], v[24:27], v[228:231], v[84:87]
	v_mfma_f32_16x16x32_bf16 v[84:87], v[204:207], v[234:237], v[64:67]
	v_mfma_f32_16x16x32_bf16 v[64:67], v[12:15], v[238:241], v[88:91]
	v_mfma_f32_16x16x32_bf16 v[76:79], v[16:19], v[242:245], v[64:67]
	v_mfma_f32_16x16x32_bf16 v[64:67], v[24:27], v[238:241], v[98:101]
	v_mfma_f32_16x16x32_bf16 v[68:71], v[204:207], v[242:245], v[64:67]
	s_setprio 0
	s_setprio 1
	v_mfma_f32_16x16x32_bf16 v[64:67], v[208:211], v[20:23], v[106:109]
	v_mfma_f32_16x16x32_bf16 v[20:23], v[216:219], v[20:23], v[32:35]
	v_mfma_f32_16x16x32_bf16 v[114:117], v[220:223], v[28:31], v[20:23]
	v_mfma_f32_16x16x32_bf16 v[20:23], v[208:211], v[60:63], v[36:39]
	v_mfma_f32_16x16x32_bf16 v[106:109], v[212:215], v[224:227], v[20:23]
	v_mfma_f32_16x16x32_bf16 v[20:23], v[216:219], v[60:63], v[40:43]
	v_mfma_f32_16x16x32_bf16 v[98:101], v[220:223], v[224:227], v[20:23]
	v_mfma_f32_16x16x32_bf16 v[20:23], v[208:211], v[228:231], v[44:47]
	v_mfma_f32_16x16x32_bf16 v[88:91], v[212:215], v[234:237], v[20:23]
	v_mfma_f32_16x16x32_bf16 v[20:23], v[216:219], v[228:231], v[48:51]
	v_mfma_f32_16x16x32_bf16 v[80:83], v[220:223], v[234:237], v[20:23]
	v_mfma_f32_16x16x32_bf16 v[20:23], v[208:211], v[238:241], v[52:55]
	v_mfma_f32_16x16x32_bf16 v[72:75], v[212:215], v[242:245], v[20:23]
	v_mfma_f32_16x16x32_bf16 v[20:23], v[216:219], v[238:241], v[56:59]
	v_mfma_f32_16x16x32_bf16 v[122:125], v[212:215], v[28:31], v[64:67]
	v_mfma_f32_16x16x32_bf16 v[64:67], v[220:223], v[242:245], v[20:23]
	s_setprio 0
	s_barrier
; template <class Epi, class Sched, bool ALIGN_EPI = false, bool SP2 = false>
; __device__ __forceinline__ void gemm_phase(PG8_LAS unsigned char* lds, const Gemm g, const Sched& S, const Epi& E) {
;     ...
;         if constexpr (Epi::PEEL) {
;             const char* a1 = cA + kstepA; const char* a2 = cA + 2 * kstepA; const char* b2 = cB + 2 * kstepB; const char* a3 = a2 + kstepA; const char* b3 = b2 + kstepB;
;             PG8_ITER(8);
;         }
	s_mov_b64 s[2:3], 0x180
	s_add_i32 s30, s30, s10
	s_nop 1
	v_lshl_add_u64 v[20:21], v[158:159], 0, s[2:3]
	s_mov_b32 m0, s30
	s_add_i32 s31, s30, 0x2000
	ds_read_b128 v[32:35], v161 offset:49152
	ds_read_b128 v[40:43], v161 offset:50176
	ds_read_b128 v[224:227], v161 offset:51200
	ds_read_b128 v[228:231], v161 offset:52224
	ds_read_b128 v[234:237], v161 offset:53248
	ds_read_b128 v[238:241], v161 offset:54272
	ds_read_b128 v[242:245], v161 offset:55296
	ds_read_b128 v[246:249], v161 offset:56320
	global_load_lds_dwordx4 v[20:21], off
	v_lshl_add_u64 v[20:21], v[178:179], 0, s[2:3]
	s_add_u32 s2, s0, 0x40180
	s_mov_b32 m0, s31
	s_addc_u32 s3, s1, 0
	s_add_i32 s57, s57, s10
	global_load_lds_dwordx4 v[20:21], off
	s_mov_b32 m0, s57
	s_add_i32 s96, s57, 0x2000
	global_load_lds_dwordx4 v132, s[2:3]
	s_mov_b32 m0, s96
	s_nop 0
	global_load_lds_dwordx4 v136, s[2:3]
	s_mov_b32 m0, s11
	s_nop 0
	global_load_lds_dwordx4 v130, s[42:43]
	s_mov_b32 m0, s19
	s_nop 0
	global_load_lds_dwordx4 v134, s[42:43]
	s_waitcnt vmcnt(8)
	s_waitcnt lgkmcnt(0)
	s_barrier
	s_setprio 1
	s_waitcnt lgkmcnt(0)
	v_mfma_f32_16x16x32_bf16 v[20:23], v[12:15], v[32:35], v[146:149]
	v_mfma_f32_16x16x32_bf16 v[60:63], v[16:19], v[40:43], v[20:23]
	v_mfma_f32_16x16x32_bf16 v[20:23], v[24:27], v[32:35], v[150:153]
	v_mfma_f32_16x16x32_bf16 v[52:55], v[204:207], v[40:43], v[20:23]
	v_mfma_f32_16x16x32_bf16 v[20:23], v[12:15], v[224:227], v[154:157]
	v_mfma_f32_16x16x32_bf16 v[44:47], v[16:19], v[228:231], v[20:23]
	v_mfma_f32_16x16x32_bf16 v[20:23], v[24:27], v[224:227], v[162:165]
	v_mfma_f32_16x16x32_bf16 v[36:39], v[204:207], v[228:231], v[20:23]
	v_mfma_f32_16x16x32_bf16 v[20:23], v[12:15], v[234:237], v[166:169]
	v_mfma_f32_16x16x32_bf16 v[0:3], v[12:15], v[242:245], v[0:3]
	v_mfma_f32_16x16x32_bf16 v[28:31], v[16:19], v[238:241], v[20:23]
	v_mfma_f32_16x16x32_bf16 v[20:23], v[24:27], v[234:237], v[170:173]
	v_mfma_f32_16x16x32_bf16 v[12:15], v[16:19], v[246:249], v[0:3]
	v_mfma_f32_16x16x32_bf16 v[0:3], v[24:27], v[242:245], v[4:7]
	v_mfma_f32_16x16x32_bf16 v[20:23], v[204:207], v[238:241], v[20:23]
	v_mfma_f32_16x16x32_bf16 v[4:7], v[204:207], v[246:249], v[0:3]
	s_setprio 0
	s_setprio 1
	v_mfma_f32_16x16x32_bf16 v[0:3], v[208:211], v[32:35], v[8:11]
	v_mfma_f32_16x16x32_bf16 v[56:59], v[212:215], v[40:43], v[0:3]
	v_mfma_f32_16x16x32_bf16 v[0:3], v[216:219], v[32:35], v[174:177]
	v_mfma_f32_16x16x32_bf16 v[48:51], v[220:223], v[40:43], v[0:3]
	v_mfma_f32_16x16x32_bf16 v[0:3], v[208:211], v[224:227], v[180:183]
	v_mfma_f32_16x16x32_bf16 v[40:43], v[212:215], v[228:231], v[0:3]
	v_mfma_f32_16x16x32_bf16 v[0:3], v[216:219], v[224:227], v[184:187]
	v_mfma_f32_16x16x32_bf16 v[32:35], v[220:223], v[228:231], v[0:3]
	v_mfma_f32_16x16x32_bf16 v[0:3], v[208:211], v[234:237], v[188:191]
	v_mfma_f32_16x16x32_bf16 v[24:27], v[212:215], v[238:241], v[0:3]
	v_mfma_f32_16x16x32_bf16 v[0:3], v[216:219], v[234:237], v[192:195]
	v_mfma_f32_16x16x32_bf16 v[16:19], v[220:223], v[238:241], v[0:3]
	v_mfma_f32_16x16x32_bf16 v[0:3], v[208:211], v[242:245], v[196:199]
	v_mfma_f32_16x16x32_bf16 v[8:11], v[212:215], v[246:249], v[0:3]
	v_mfma_f32_16x16x32_bf16 v[0:3], v[216:219], v[242:245], v[200:203]
	v_mfma_f32_16x16x32_bf16 v[0:3], v[220:223], v[246:249], v[0:3]
	s_setprio 0
	s_barrier
	s_add_u32 s3, s0, 0x200
	s_addc_u32 s2, s1, 0
	s_add_u32 s0, s24, 0xc04000
	s_addc_u32 s1, s25, 0
	s_mov_b32 s18, 0

; template <class Epi, class Sched, bool ALIGN_EPI = false, bool SP2 = false>
; __device__ __forceinline__ void gemm_phase(PG8_LAS unsigned char* lds, const Gemm g, const Sched& S, const Epi& E) {
;     ...
;         if constexpr (Epi::PEEL) {
;             const char* a1 = cA + kstepA; const char* a2 = cA + 2 * kstepA; const char* b2 = cB + 2 * kstepB; const char* a3 = a2 + kstepA; const char* b3 = b2 + kstepB;
;             PG8_ITER(8);
;         }
.LBB0_249:
	s_ashr_i32 s49, s48, 31
	s_lshl_b64 s[2:3], s[48:49], 15
	v_readlane_b32 s11, v255, 15
	s_add_u32 s50, s11, s2
	v_readlane_b32 s2, v255, 16
	s_addc_u32 s51, s2, s3
	s_ashr_i32 s47, s46, 31
	s_lshl_b64 s[2:3], s[46:47], 19
	s_add_u32 s52, s38, s2
	s_addc_u32 s53, s19, s3
	s_add_u32 s28, s42, 0x800000
	s_addc_u32 s29, s43, 0
	s_add_u32 s44, s42, 0xc00000
	s_addc_u32 s45, s43, 0
	s_add_i32 s99, 0, 0x10000
	s_and_b64 s[2:3], s[40:41], exec
	s_cselect_b32 s27, s51, s43
	s_cselect_b32 s47, s50, s42
	s_add_i32 vcc_hi, 0, 0x14000
	v_add_u32_e32 v130, s99, v97
	v_add_u32_e32 v131, vcc_hi, v97
	ds_read_b128 v[0:3], v130
	ds_read_b128 v[4:7], v130 offset:1024
	ds_read_b128 v[8:11], v130 offset:2048
	ds_read_b128 v[12:15], v130 offset:3072
	ds_read_b128 v[16:19], v131
	s_waitcnt lgkmcnt(0)
	ds_read_b128 v[20:23], v131 offset:1024
	ds_read_b128 v[24:27], v131 offset:2048
	ds_read_b128 v[28:31], v131 offset:3072
	s_and_b64 s[2:3], s[40:41], exec
	s_cselect_b32 s49, s53, s25
	s_cselect_b32 s54, s52, s24
	s_add_u32 s2, s42, 0x404000
	s_addc_u32 s3, s43, 0
	s_add_i32 s55, s22, 0xc000
	s_mov_b32 m0, s55
	s_add_i32 s98, s22, 0xe000
	ds_read_b128 v[32:35], v151
	ds_read_b128 v[36:39], v151 offset:1024
	ds_read_b128 v[40:43], v151 offset:2048
	ds_read_b128 v[44:47], v151 offset:3072
	ds_read_b128 v[48:51], v151 offset:4096
	ds_read_b128 v[52:55], v151 offset:5120
	ds_read_b128 v[56:59], v151 offset:6144
	ds_read_b128 v[60:63], v151 offset:7168
	global_load_lds_dwordx4 v134, s[2:3]
	s_mov_b32 m0, s98
	s_nop 0
	global_load_lds_dwordx4 v138, s[2:3]
	s_waitcnt vmcnt(8)
	s_waitcnt lgkmcnt(0)
	s_barrier
	s_setprio 1
	s_waitcnt lgkmcnt(0)
	v_mfma_f32_16x16x32_bf16 v[84:87], v[8:11], v[48:51], 0
	v_mfma_f32_16x16x32_bf16 v[88:91], v[12:15], v[52:55], v[84:87]
	v_mfma_f32_16x16x32_bf16 v[84:87], v[0:3], v[56:59], 0
	v_mfma_f32_16x16x32_bf16 v[64:67], v[0:3], v[32:35], 0
	v_mfma_f32_16x16x32_bf16 v[68:71], v[8:11], v[32:35], 0
	v_mfma_f32_16x16x32_bf16 v[72:75], v[0:3], v[40:43], 0
	v_mfma_f32_16x16x32_bf16 v[76:79], v[8:11], v[40:43], 0
	v_mfma_f32_16x16x32_bf16 v[80:83], v[0:3], v[48:51], 0
	v_mfma_f32_16x16x32_bf16 v[92:95], v[4:7], v[60:63], v[84:87]
	v_mfma_f32_16x16x32_bf16 v[84:87], v[8:11], v[56:59], 0
	v_mfma_f32_16x16x32_bf16 v[64:67], v[4:7], v[36:39], v[64:67]
	v_mfma_f32_16x16x32_bf16 v[68:71], v[12:15], v[36:39], v[68:71]
	v_mfma_f32_16x16x32_bf16 v[72:75], v[4:7], v[44:47], v[72:75]
	v_mfma_f32_16x16x32_bf16 v[76:79], v[12:15], v[44:47], v[76:79]
	v_mfma_f32_16x16x32_bf16 v[80:83], v[4:7], v[52:55], v[80:83]
	v_mfma_f32_16x16x32_bf16 v[106:109], v[12:15], v[60:63], v[84:87]
	s_setprio 0
	s_setprio 1
	v_mfma_f32_16x16x32_bf16 v[84:87], v[16:19], v[32:35], 0
	v_mfma_f32_16x16x32_bf16 v[32:35], v[24:27], v[32:35], 0
	v_mfma_f32_16x16x32_bf16 v[110:113], v[20:23], v[36:39], v[84:87]
	v_mfma_f32_16x16x32_bf16 v[32:35], v[28:31], v[36:39], v[32:35]
	v_mfma_f32_16x16x32_bf16 v[36:39], v[16:19], v[40:43], 0
	v_mfma_f32_16x16x32_bf16 v[40:43], v[24:27], v[40:43], 0
	v_mfma_f32_16x16x32_bf16 v[36:39], v[20:23], v[44:47], v[36:39]
	v_mfma_f32_16x16x32_bf16 v[40:43], v[28:31], v[44:47], v[40:43]
	v_mfma_f32_16x16x32_bf16 v[44:47], v[16:19], v[48:51], 0
	v_mfma_f32_16x16x32_bf16 v[48:51], v[24:27], v[48:51], 0
	v_mfma_f32_16x16x32_bf16 v[44:47], v[20:23], v[52:55], v[44:47]
	v_mfma_f32_16x16x32_bf16 v[48:51], v[28:31], v[52:55], v[48:51]
	v_mfma_f32_16x16x32_bf16 v[52:55], v[16:19], v[56:59], 0
	v_mfma_f32_16x16x32_bf16 v[56:59], v[24:27], v[56:59], 0
	v_mfma_f32_16x16x32_bf16 v[52:55], v[20:23], v[60:63], v[52:55]
	v_mfma_f32_16x16x32_bf16 v[56:59], v[28:31], v[60:63], v[56:59]
	s_setprio 0
	s_barrier
	v_lshl_add_u64 v[176:177], s[24:25], 0, v[136:137]
	s_mov_b64 s[2:3], 0x100
	s_add_i32 s99, s99, s10
	v_lshl_add_u64 v[132:133], v[176:177], 0, s[2:3]
	s_mov_b32 m0, s99
	v_lshl_add_u64 v[178:179], s[24:25], 0, v[140:141]
	s_add_i32 vcc_lo, s99, 0x2000
	ds_read_b128 v[60:63], v151 offset:16384
	ds_read_b128 v[84:87], v151 offset:17408
	ds_read_b128 v[98:101], v151 offset:18432
	ds_read_b128 v[102:105], v151 offset:19456
	ds_read_b128 v[114:117], v151 offset:20480
	ds_read_b128 v[118:121], v151 offset:21504
	ds_read_b128 v[122:125], v151 offset:22528
	ds_read_b128 v[126:129], v151 offset:23552
	global_load_lds_dwordx4 v[132:133], off
	v_lshl_add_u64 v[132:133], v[178:179], 0, s[2:3]
	s_add_u32 s2, s24, 0x40100
	s_mov_b32 m0, vcc_lo
	s_addc_u32 s3, s25, 0
	s_add_i32 vcc_hi, vcc_hi, s10
	global_load_lds_dwordx4 v[132:133], off
	s_mov_b32 m0, vcc_hi
	s_add_i32 s30, vcc_hi, 0x2000
	global_load_lds_dwordx4 v136, s[2:3]
	s_mov_b32 m0, s30
	s_mov_b64 s[34:35], 0x100
	global_load_lds_dwordx4 v140, s[2:3]
	s_mov_b32 m0, s22
	s_nop 0
	global_load_lds_dwordx4 v134, s[28:29]
	s_mov_b32 m0, s23
	s_nop 0
	global_load_lds_dwordx4 v138, s[28:29]
	s_waitcnt vmcnt(8)
	s_waitcnt lgkmcnt(0)
	s_barrier
; template <class Epi, class Sched, bool ALIGN_EPI = false, bool SP2 = false>
; __device__ __forceinline__ void gemm_phase(PG8_LAS unsigned char* lds, const Gemm g, const Sched& S, const Epi& E) {
;     ...
;         if constexpr (Epi::PEEL) {
;             const char* a1 = cA + kstepA; const char* a2 = cA + 2 * kstepA; const char* b2 = cB + 2 * kstepB; const char* a3 = a2 + kstepA; const char* b3 = b2 + kstepB;
;             PG8_ITER(8);
;         }
	s_setprio 1
	s_waitcnt lgkmcnt(0)
	v_mfma_f32_16x16x32_bf16 v[146:149], v[0:3], v[60:63], 0
	v_mfma_f32_16x16x32_bf16 v[156:159], v[0:3], v[98:101], 0
	v_mfma_f32_16x16x32_bf16 v[164:167], v[0:3], v[114:117], 0
	v_mfma_f32_16x16x32_bf16 v[0:3], v[0:3], v[122:125], 0
	v_mfma_f32_16x16x32_bf16 v[146:149], v[4:7], v[84:87], v[146:149]
	v_mfma_f32_16x16x32_bf16 v[156:159], v[4:7], v[102:105], v[156:159]
	v_mfma_f32_16x16x32_bf16 v[164:167], v[4:7], v[118:121], v[164:167]
	v_mfma_f32_16x16x32_bf16 v[0:3], v[4:7], v[126:129], v[0:3]
	v_mfma_f32_16x16x32_bf16 v[4:7], v[8:11], v[122:125], 0
	v_mfma_f32_16x16x32_bf16 v[152:155], v[8:11], v[60:63], 0
	v_mfma_f32_16x16x32_bf16 v[160:163], v[8:11], v[98:101], 0
	v_mfma_f32_16x16x32_bf16 v[168:171], v[8:11], v[114:117], 0
	v_mfma_f32_16x16x32_bf16 v[8:11], v[12:15], v[126:129], v[4:7]
	v_mfma_f32_16x16x32_bf16 v[152:155], v[12:15], v[84:87], v[152:155]
	v_mfma_f32_16x16x32_bf16 v[160:163], v[12:15], v[102:105], v[160:163]
	v_mfma_f32_16x16x32_bf16 v[168:171], v[12:15], v[118:121], v[168:171]
	s_setprio 0
	s_setprio 1
	v_mfma_f32_16x16x32_bf16 v[4:7], v[16:19], v[60:63], 0
	v_mfma_f32_16x16x32_bf16 v[12:15], v[20:23], v[84:87], v[4:7]
	v_mfma_f32_16x16x32_bf16 v[4:7], v[24:27], v[60:63], 0
	v_mfma_f32_16x16x32_bf16 v[172:175], v[28:31], v[84:87], v[4:7]
	v_mfma_f32_16x16x32_bf16 v[4:7], v[16:19], v[98:101], 0
	v_mfma_f32_16x16x32_bf16 v[180:183], v[20:23], v[102:105], v[4:7]
	v_mfma_f32_16x16x32_bf16 v[4:7], v[24:27], v[98:101], 0
	v_mfma_f32_16x16x32_bf16 v[184:187], v[28:31], v[102:105], v[4:7]
	v_mfma_f32_16x16x32_bf16 v[4:7], v[16:19], v[114:117], 0
	v_mfma_f32_16x16x32_bf16 v[188:191], v[20:23], v[118:121], v[4:7]
	v_mfma_f32_16x16x32_bf16 v[4:7], v[24:27], v[114:117], 0
	v_mfma_f32_16x16x32_bf16 v[192:195], v[28:31], v[118:121], v[4:7]
	v_mfma_f32_16x16x32_bf16 v[4:7], v[16:19], v[122:125], 0
	v_mfma_f32_16x16x32_bf16 v[196:199], v[20:23], v[126:129], v[4:7]
	v_mfma_f32_16x16x32_bf16 v[4:7], v[24:27], v[122:125], 0
	v_mfma_f32_16x16x32_bf16 v[200:203], v[28:31], v[126:129], v[4:7]
	s_setprio 0
	s_barrier
	s_add_i32 s31, 0, 0x18000
	s_add_i32 s13, 0, 0x1c000
	v_add_u32_e32 v132, s31, v97
	v_add_u32_e32 v133, s13, v97
	s_nop 0
	ds_read_b128 v[4:7], v132
	ds_read_b128 v[24:27], v132 offset:1024
	ds_read_b128 v[28:31], v132 offset:2048
	ds_read_b128 v[60:63], v132 offset:3072
	ds_read_b128 v[204:207], v133
	ds_read_b128 v[208:211], v133 offset:1024
	ds_read_b128 v[212:215], v133 offset:2048
	ds_read_b128 v[216:219], v133 offset:3072
	s_add_u32 s2, s42, 0x804000
	s_addc_u32 s3, s43, 0
	s_mov_b32 m0, s39
	ds_read_b128 v[16:19], v151 offset:32768
	ds_read_b128 v[20:23], v151 offset:33792
	ds_read_b128 v[220:223], v151 offset:34816
	ds_read_b128 v[224:227], v151 offset:35840
	ds_read_b128 v[228:231], v151 offset:36864
	ds_read_b128 v[234:237], v151 offset:37888
	ds_read_b128 v[238:241], v151 offset:38912
	ds_read_b128 v[242:245], v151 offset:39936
	global_load_lds_dwordx4 v134, s[2:3]
	s_mov_b32 m0, s56
	s_nop 0
	global_load_lds_dwordx4 v138, s[2:3]
	s_waitcnt vmcnt(8)
	s_waitcnt lgkmcnt(0)
	s_barrier
	s_setprio 1
	s_waitcnt lgkmcnt(0)
	v_mfma_f32_16x16x32_bf16 v[64:67], v[4:7], v[16:19], v[64:67]
	v_mfma_f32_16x16x32_bf16 v[118:121], v[24:27], v[20:23], v[64:67]
	v_mfma_f32_16x16x32_bf16 v[64:67], v[28:31], v[16:19], v[68:71]
	v_mfma_f32_16x16x32_bf16 v[114:117], v[60:63], v[20:23], v[64:67]
	v_mfma_f32_16x16x32_bf16 v[64:67], v[4:7], v[220:223], v[72:75]
	v_mfma_f32_16x16x32_bf16 v[102:105], v[24:27], v[224:227], v[64:67]
	v_mfma_f32_16x16x32_bf16 v[64:67], v[28:31], v[220:223], v[76:79]
	v_mfma_f32_16x16x32_bf16 v[98:101], v[60:63], v[224:227], v[64:67]
	v_mfma_f32_16x16x32_bf16 v[64:67], v[4:7], v[228:231], v[80:83]
	v_mfma_f32_16x16x32_bf16 v[84:87], v[24:27], v[234:237], v[64:67]
	v_mfma_f32_16x16x32_bf16 v[64:67], v[28:31], v[228:231], v[88:91]
	v_mfma_f32_16x16x32_bf16 v[80:83], v[60:63], v[234:237], v[64:67]
	v_mfma_f32_16x16x32_bf16 v[64:67], v[4:7], v[238:241], v[92:95]
	v_mfma_f32_16x16x32_bf16 v[68:71], v[24:27], v[242:245], v[64:67]
	v_mfma_f32_16x16x32_bf16 v[64:67], v[28:31], v[238:241], v[106:109]
	v_mfma_f32_16x16x32_bf16 v[64:67], v[60:63], v[242:245], v[64:67]
	s_setprio 0
	s_setprio 1
	v_mfma_f32_16x16x32_bf16 v[72:75], v[204:207], v[16:19], v[110:113]
	v_mfma_f32_16x16x32_bf16 v[16:19], v[212:215], v[16:19], v[32:35]
	v_mfma_f32_16x16x32_bf16 v[122:125], v[216:219], v[20:23], v[16:19]
	v_mfma_f32_16x16x32_bf16 v[16:19], v[204:207], v[220:223], v[36:39]
	v_mfma_f32_16x16x32_bf16 v[110:113], v[208:211], v[224:227], v[16:19]
	v_mfma_f32_16x16x32_bf16 v[16:19], v[212:215], v[220:223], v[40:43]
	v_mfma_f32_16x16x32_bf16 v[106:109], v[216:219], v[224:227], v[16:19]
	v_mfma_f32_16x16x32_bf16 v[16:19], v[204:207], v[228:231], v[44:47]
	v_mfma_f32_16x16x32_bf16 v[92:95], v[208:211], v[234:237], v[16:19]
	v_mfma_f32_16x16x32_bf16 v[16:19], v[212:215], v[228:231], v[48:51]
	v_mfma_f32_16x16x32_bf16 v[88:91], v[216:219], v[234:237], v[16:19]
	v_mfma_f32_16x16x32_bf16 v[16:19], v[204:207], v[238:241], v[52:55]
	v_mfma_f32_16x16x32_bf16 v[76:79], v[208:211], v[242:245], v[16:19]
	v_mfma_f32_16x16x32_bf16 v[16:19], v[212:215], v[238:241], v[56:59]
	v_mfma_f32_16x16x32_bf16 v[126:129], v[208:211], v[20:23], v[72:75]
	v_mfma_f32_16x16x32_bf16 v[72:75], v[216:219], v[242:245], v[16:19]
	s_setprio 0
	s_barrier
; template <class Epi, class Sched, bool ALIGN_EPI = false, bool SP2 = false>
; __device__ __forceinline__ void gemm_phase(PG8_LAS unsigned char* lds, const Gemm g, const Sched& S, const Epi& E) {
;     ...
;         if constexpr (Epi::PEEL) {
;             const char* a1 = cA + kstepA; const char* a2 = cA + 2 * kstepA; const char* b2 = cB + 2 * kstepB; const char* a3 = a2 + kstepA; const char* b3 = b2 + kstepB;
;             PG8_ITER(8);
;         }
	s_mov_b64 s[2:3], 0x180
	s_add_i32 s31, s31, s10
	s_nop 1
	v_lshl_add_u64 v[16:17], v[176:177], 0, s[2:3]
	s_mov_b32 m0, s31
	s_add_i32 s12, s31, 0x2000
	ds_read_b128 v[40:43], v151 offset:49152
	ds_read_b128 v[44:47], v151 offset:50176
	ds_read_b128 v[220:223], v151 offset:51200
	ds_read_b128 v[224:227], v151 offset:52224
	ds_read_b128 v[228:231], v151 offset:53248
	ds_read_b128 v[234:237], v151 offset:54272
	ds_read_b128 v[238:241], v151 offset:55296
	ds_read_b128 v[242:245], v151 offset:56320
	global_load_lds_dwordx4 v[16:17], off
	v_lshl_add_u64 v[16:17], v[178:179], 0, s[2:3]
	s_add_u32 s2, s24, 0x40180
	s_mov_b32 m0, s12
	s_addc_u32 s3, s25, 0
	s_add_i32 s13, s13, s10
	global_load_lds_dwordx4 v[16:17], off
	s_mov_b32 m0, s13
	s_add_i32 s11, s13, 0x2000
	global_load_lds_dwordx4 v136, s[2:3]
	s_mov_b32 m0, s11
	s_nop 0
	global_load_lds_dwordx4 v140, s[2:3]
	s_mov_b32 m0, s59
	s_nop 0
	global_load_lds_dwordx4 v134, s[44:45]
	s_mov_b32 m0, s96
	s_nop 0
	global_load_lds_dwordx4 v138, s[44:45]
	s_waitcnt vmcnt(8)
	s_waitcnt lgkmcnt(0)
	s_barrier
	s_setprio 1
	s_waitcnt lgkmcnt(0)
	v_mfma_f32_16x16x32_bf16 v[16:19], v[4:7], v[40:43], v[146:149]
	v_mfma_f32_16x16x32_bf16 v[52:55], v[24:27], v[44:47], v[16:19]
	v_mfma_f32_16x16x32_bf16 v[16:19], v[28:31], v[40:43], v[152:155]
	v_mfma_f32_16x16x32_bf16 v[48:51], v[60:63], v[44:47], v[16:19]
	v_mfma_f32_16x16x32_bf16 v[16:19], v[4:7], v[220:223], v[156:159]
	v_mfma_f32_16x16x32_bf16 v[36:39], v[24:27], v[224:227], v[16:19]
	v_mfma_f32_16x16x32_bf16 v[16:19], v[28:31], v[220:223], v[160:163]
	v_mfma_f32_16x16x32_bf16 v[32:35], v[60:63], v[224:227], v[16:19]
	v_mfma_f32_16x16x32_bf16 v[16:19], v[4:7], v[228:231], v[164:167]
	v_mfma_f32_16x16x32_bf16 v[0:3], v[4:7], v[238:241], v[0:3]
	v_mfma_f32_16x16x32_bf16 v[20:23], v[24:27], v[234:237], v[16:19]
	v_mfma_f32_16x16x32_bf16 v[16:19], v[28:31], v[228:231], v[168:171]
	v_mfma_f32_16x16x32_bf16 v[4:7], v[24:27], v[242:245], v[0:3]
	v_mfma_f32_16x16x32_bf16 v[0:3], v[28:31], v[238:241], v[8:11]
	v_mfma_f32_16x16x32_bf16 v[16:19], v[60:63], v[234:237], v[16:19]
	v_mfma_f32_16x16x32_bf16 v[0:3], v[60:63], v[242:245], v[0:3]
	s_setprio 0
	s_setprio 1
	v_mfma_f32_16x16x32_bf16 v[8:11], v[204:207], v[40:43], v[12:15]
	v_mfma_f32_16x16x32_bf16 v[60:63], v[208:211], v[44:47], v[8:11]
	v_mfma_f32_16x16x32_bf16 v[8:11], v[212:215], v[40:43], v[172:175]
	v_mfma_f32_16x16x32_bf16 v[56:59], v[216:219], v[44:47], v[8:11]
	v_mfma_f32_16x16x32_bf16 v[8:11], v[204:207], v[220:223], v[180:183]
	v_mfma_f32_16x16x32_bf16 v[44:47], v[208:211], v[224:227], v[8:11]
	v_mfma_f32_16x16x32_bf16 v[8:11], v[212:215], v[220:223], v[184:187]
	v_mfma_f32_16x16x32_bf16 v[40:43], v[216:219], v[224:227], v[8:11]
	v_mfma_f32_16x16x32_bf16 v[8:11], v[204:207], v[228:231], v[188:191]
	v_mfma_f32_16x16x32_bf16 v[28:31], v[208:211], v[234:237], v[8:11]
	v_mfma_f32_16x16x32_bf16 v[8:11], v[212:215], v[228:231], v[192:195]
	v_mfma_f32_16x16x32_bf16 v[24:27], v[216:219], v[234:237], v[8:11]
	v_mfma_f32_16x16x32_bf16 v[8:11], v[204:207], v[238:241], v[196:199]
	v_mfma_f32_16x16x32_bf16 v[12:15], v[208:211], v[242:245], v[8:11]
	v_mfma_f32_16x16x32_bf16 v[8:11], v[212:215], v[238:241], v[200:203]
	v_mfma_f32_16x16x32_bf16 v[8:11], v[216:219], v[242:245], v[8:11]
	s_setprio 0
	s_barrier
	s_add_u32 s3, s24, 0x200
	s_addc_u32 s2, s25, 0
	s_add_u32 s24, s42, 0xc04000
	s_addc_u32 s25, s43, 0
	s_mov_b32 s18, 0

; template <class Epi, class Sched, bool ALIGN_EPI = false, bool SP2 = false>
; __device__ __forceinline__ void gemm_phase(PG8_LAS unsigned char* lds, const Gemm g, const Sched& S, const Epi& E) {
;     ...
;         if constexpr (Epi::PEEL) {
;             const char* a1 = cA + kstepA; const char* a2 = cA + 2 * kstepA; const char* b2 = cB + 2 * kstepB; const char* a3 = a2 + kstepA; const char* b3 = b2 + kstepB;
;             PG8_ITER(8);
;         }
.LBB0_477:
	s_ashr_i32 s27, s26, 31
	s_lshl_b64 s[2:3], s[26:27], 15
	v_readlane_b32 s10, v255, 15
	s_add_u32 s28, s10, s2
	v_readlane_b32 s2, v255, 16
	s_addc_u32 s29, s2, s3
	s_ashr_i32 s25, s24, 31
	s_lshl_b64 s[2:3], s[24:25], 19
	s_add_u32 s30, s19, s2
	s_addc_u32 s31, s22, s3
	s_add_u32 s44, s34, 0x800000
	s_addc_u32 s45, s35, 0
	s_add_u32 s42, s34, 0xc00000
	s_addc_u32 s43, s35, 0
	s_add_i32 s61, 0, 0x10000
	s_and_b64 s[2:3], s[40:41], exec
	s_cselect_b32 s25, s29, s35
	s_cselect_b32 s27, s28, s34
	s_add_i32 s97, 0, 0x14000
	v_add_u32_e32 v142, s61, v97
	v_add_u32_e32 v143, s97, v97
	ds_read_b128 v[0:3], v142
	ds_read_b128 v[4:7], v142 offset:1024
	ds_read_b128 v[8:11], v142 offset:2048
	ds_read_b128 v[12:15], v142 offset:3072
	ds_read_b128 v[16:19], v143
	s_waitcnt lgkmcnt(0)
	ds_read_b128 v[20:23], v143 offset:1024
	ds_read_b128 v[24:27], v143 offset:2048
	ds_read_b128 v[28:31], v143 offset:3072
	s_and_b64 s[2:3], s[40:41], exec
	s_cselect_b32 s57, s31, s1
	s_cselect_b32 s58, s30, s0
	s_add_u32 s2, s34, 0x404000
	s_addc_u32 s3, s35, 0
	s_add_i32 s59, s23, 0xc000
	s_mov_b32 m0, s59
	s_add_i32 s60, s23, 0xe000
	ds_read_b128 v[32:35], v156
	ds_read_b128 v[36:39], v156 offset:1024
	ds_read_b128 v[40:43], v156 offset:2048
	ds_read_b128 v[44:47], v156 offset:3072
	ds_read_b128 v[48:51], v156 offset:4096
	ds_read_b128 v[52:55], v156 offset:5120
	ds_read_b128 v[56:59], v156 offset:6144
	ds_read_b128 v[60:63], v156 offset:7168
	global_load_lds_dwordx4 v130, s[2:3]
	s_mov_b32 m0, s60
	s_nop 0
	global_load_lds_dwordx4 v134, s[2:3]
	s_waitcnt vmcnt(8)
	s_waitcnt lgkmcnt(0)
	s_barrier
	s_setprio 1
	s_waitcnt lgkmcnt(0)
	v_mfma_f32_16x16x32_bf16 v[88:91], v[0:3], v[56:59], 0
	v_mfma_f32_16x16x32_bf16 v[64:67], v[0:3], v[32:35], 0
	v_mfma_f32_16x16x32_bf16 v[68:71], v[8:11], v[32:35], 0
	v_mfma_f32_16x16x32_bf16 v[72:75], v[0:3], v[40:43], 0
	v_mfma_f32_16x16x32_bf16 v[76:79], v[8:11], v[40:43], 0
	v_mfma_f32_16x16x32_bf16 v[80:83], v[0:3], v[48:51], 0
	v_mfma_f32_16x16x32_bf16 v[84:87], v[8:11], v[48:51], 0
	v_mfma_f32_16x16x32_bf16 v[92:95], v[4:7], v[60:63], v[88:91]
	v_mfma_f32_16x16x32_bf16 v[88:91], v[8:11], v[56:59], 0
	v_mfma_f32_16x16x32_bf16 v[64:67], v[4:7], v[36:39], v[64:67]
	v_mfma_f32_16x16x32_bf16 v[68:71], v[12:15], v[36:39], v[68:71]
	v_mfma_f32_16x16x32_bf16 v[72:75], v[4:7], v[44:47], v[72:75]
	v_mfma_f32_16x16x32_bf16 v[76:79], v[12:15], v[44:47], v[76:79]
	v_mfma_f32_16x16x32_bf16 v[80:83], v[4:7], v[52:55], v[80:83]
	v_mfma_f32_16x16x32_bf16 v[84:87], v[12:15], v[52:55], v[84:87]
	v_mfma_f32_16x16x32_bf16 v[102:105], v[12:15], v[60:63], v[88:91]
	s_setprio 0
	s_setprio 1
	v_mfma_f32_16x16x32_bf16 v[88:91], v[16:19], v[32:35], 0
	v_mfma_f32_16x16x32_bf16 v[32:35], v[24:27], v[32:35], 0
	v_mfma_f32_16x16x32_bf16 v[110:113], v[20:23], v[36:39], v[88:91]
	v_mfma_f32_16x16x32_bf16 v[32:35], v[28:31], v[36:39], v[32:35]
	v_mfma_f32_16x16x32_bf16 v[36:39], v[16:19], v[40:43], 0
	v_mfma_f32_16x16x32_bf16 v[40:43], v[24:27], v[40:43], 0
	v_mfma_f32_16x16x32_bf16 v[36:39], v[20:23], v[44:47], v[36:39]
	v_mfma_f32_16x16x32_bf16 v[40:43], v[28:31], v[44:47], v[40:43]
	v_mfma_f32_16x16x32_bf16 v[44:47], v[16:19], v[48:51], 0
	v_mfma_f32_16x16x32_bf16 v[48:51], v[24:27], v[48:51], 0
	v_mfma_f32_16x16x32_bf16 v[44:47], v[20:23], v[52:55], v[44:47]
	v_mfma_f32_16x16x32_bf16 v[48:51], v[28:31], v[52:55], v[48:51]
	v_mfma_f32_16x16x32_bf16 v[52:55], v[16:19], v[56:59], 0
	v_mfma_f32_16x16x32_bf16 v[56:59], v[24:27], v[56:59], 0
	v_mfma_f32_16x16x32_bf16 v[52:55], v[20:23], v[60:63], v[52:55]
	v_mfma_f32_16x16x32_bf16 v[56:59], v[28:31], v[60:63], v[56:59]
	s_setprio 0
	s_barrier
	v_lshl_add_u64 v[154:155], s[0:1], 0, v[132:133]
	s_mov_b64 s[2:3], 0x100
	s_add_i32 s61, s61, s9
	v_lshl_add_u64 v[144:145], v[154:155], 0, s[2:3]
	s_mov_b32 m0, s61
	v_lshl_add_u64 v[178:179], s[0:1], 0, v[136:137]
	s_add_i32 s96, s61, 0x2000
	ds_read_b128 v[60:63], v156 offset:16384
	ds_read_b128 v[88:91], v156 offset:17408
	ds_read_b128 v[98:101], v156 offset:18432
	ds_read_b128 v[106:109], v156 offset:19456
	ds_read_b128 v[114:117], v156 offset:20480
	ds_read_b128 v[118:121], v156 offset:21504
	ds_read_b128 v[122:125], v156 offset:22528
	ds_read_b128 v[126:129], v156 offset:23552
	global_load_lds_dwordx4 v[144:145], off
	v_lshl_add_u64 v[144:145], v[178:179], 0, s[2:3]
	s_add_u32 s2, s0, 0x40100
	s_mov_b32 m0, s96
	s_addc_u32 s3, s1, 0
	s_add_i32 s97, s97, s9
	global_load_lds_dwordx4 v[144:145], off
	s_mov_b32 m0, s97
	s_add_i32 s98, s97, 0x2000
	global_load_lds_dwordx4 v132, s[2:3]
	s_mov_b32 m0, s98
	s_nop 0
	global_load_lds_dwordx4 v136, s[2:3]
	s_mov_b32 m0, s23
	s_nop 0
	global_load_lds_dwordx4 v130, s[44:45]
	s_mov_b32 m0, s39
	s_nop 0
	global_load_lds_dwordx4 v134, s[44:45]
	s_waitcnt vmcnt(8)
	s_waitcnt lgkmcnt(0)
	s_barrier
; template <class Epi, class Sched, bool ALIGN_EPI = false, bool SP2 = false>
; __device__ __forceinline__ void gemm_phase(PG8_LAS unsigned char* lds, const Gemm g, const Sched& S, const Epi& E) {
;     ...
;         if constexpr (Epi::PEEL) {
;             const char* a1 = cA + kstepA; const char* a2 = cA + 2 * kstepA; const char* b2 = cB + 2 * kstepB; const char* a3 = a2 + kstepA; const char* b3 = b2 + kstepB;
;             PG8_ITER(8);
;         }
	s_setprio 1
	s_waitcnt lgkmcnt(0)
	v_mfma_f32_16x16x32_bf16 v[144:147], v[0:3], v[60:63], 0
	v_mfma_f32_16x16x32_bf16 v[158:161], v[0:3], v[98:101], 0
	v_mfma_f32_16x16x32_bf16 v[166:169], v[0:3], v[114:117], 0
	v_mfma_f32_16x16x32_bf16 v[0:3], v[0:3], v[122:125], 0
	v_mfma_f32_16x16x32_bf16 v[146:149], v[4:7], v[88:91], v[144:147]
	v_mfma_f32_16x16x32_bf16 v[158:161], v[4:7], v[106:109], v[158:161]
	v_mfma_f32_16x16x32_bf16 v[166:169], v[4:7], v[118:121], v[166:169]
	v_mfma_f32_16x16x32_bf16 v[0:3], v[4:7], v[126:129], v[0:3]
	v_mfma_f32_16x16x32_bf16 v[4:7], v[8:11], v[122:125], 0
	v_mfma_f32_16x16x32_bf16 v[150:153], v[8:11], v[60:63], 0
	v_mfma_f32_16x16x32_bf16 v[162:165], v[8:11], v[98:101], 0
	v_mfma_f32_16x16x32_bf16 v[170:173], v[8:11], v[114:117], 0
	v_mfma_f32_16x16x32_bf16 v[4:7], v[12:15], v[126:129], v[4:7]
	v_mfma_f32_16x16x32_bf16 v[150:153], v[12:15], v[88:91], v[150:153]
	v_mfma_f32_16x16x32_bf16 v[162:165], v[12:15], v[106:109], v[162:165]
	v_mfma_f32_16x16x32_bf16 v[170:173], v[12:15], v[118:121], v[170:173]
	s_setprio 0
	s_setprio 1
	v_mfma_f32_16x16x32_bf16 v[8:11], v[16:19], v[60:63], 0
	v_mfma_f32_16x16x32_bf16 v[12:15], v[20:23], v[88:91], v[8:11]
	v_mfma_f32_16x16x32_bf16 v[8:11], v[24:27], v[60:63], 0
	v_mfma_f32_16x16x32_bf16 v[174:177], v[28:31], v[88:91], v[8:11]
	v_mfma_f32_16x16x32_bf16 v[8:11], v[16:19], v[98:101], 0
	v_mfma_f32_16x16x32_bf16 v[188:191], v[20:23], v[106:109], v[8:11]
	v_mfma_f32_16x16x32_bf16 v[8:11], v[24:27], v[98:101], 0
	v_mfma_f32_16x16x32_bf16 v[192:195], v[28:31], v[106:109], v[8:11]
	v_mfma_f32_16x16x32_bf16 v[8:11], v[16:19], v[114:117], 0
	v_mfma_f32_16x16x32_bf16 v[196:199], v[20:23], v[118:121], v[8:11]
	v_mfma_f32_16x16x32_bf16 v[8:11], v[24:27], v[114:117], 0
	v_mfma_f32_16x16x32_bf16 v[200:203], v[28:31], v[118:121], v[8:11]
	v_mfma_f32_16x16x32_bf16 v[8:11], v[16:19], v[122:125], 0
	v_mfma_f32_16x16x32_bf16 v[204:207], v[20:23], v[126:129], v[8:11]
	v_mfma_f32_16x16x32_bf16 v[8:11], v[24:27], v[122:125], 0
	v_mfma_f32_16x16x32_bf16 v[208:211], v[28:31], v[126:129], v[8:11]
	s_setprio 0
	s_barrier
	s_add_i32 s99, 0, 0x18000
	s_add_i32 vcc_hi, 0, 0x1c000
	v_add_u32_e32 v144, s99, v97
	v_add_u32_e32 v145, vcc_hi, v97
	s_nop 0
	ds_read_b128 v[8:11], v144
	ds_read_b128 v[20:23], v144 offset:1024
	ds_read_b128 v[28:31], v144 offset:2048
	ds_read_b128 v[212:215], v144 offset:3072
	ds_read_b128 v[216:219], v145
	ds_read_b128 v[220:223], v145 offset:1024
	ds_read_b128 v[234:237], v145 offset:2048
	ds_read_b128 v[238:241], v145 offset:3072
	s_add_u32 s2, s34, 0x804000
	s_addc_u32 s3, s35, 0
	s_mov_b32 m0, s46
	ds_read_b128 v[16:19], v156 offset:32768
	ds_read_b128 v[24:27], v156 offset:33792
	ds_read_b128 v[242:245], v156 offset:34816
	ds_read_b128 v[246:249], v156 offset:35840
	ds_read_b128 v[228:231], v156 offset:36864
	ds_read_b128 v[180:183], v156 offset:37888
	ds_read_b128 v[184:187], v156 offset:38912
	ds_read_b128 v[224:227], v156 offset:39936
	global_load_lds_dwordx4 v130, s[2:3]
	s_mov_b32 m0, s47
	s_nop 0
	global_load_lds_dwordx4 v134, s[2:3]
	s_waitcnt vmcnt(8)
	s_waitcnt lgkmcnt(0)
	s_barrier
	s_setprio 1
	s_waitcnt lgkmcnt(0)
	v_mfma_f32_16x16x32_bf16 v[60:63], v[8:11], v[16:19], v[64:67]
	v_mfma_f32_16x16x32_bf16 v[122:125], v[20:23], v[24:27], v[60:63]
	v_mfma_f32_16x16x32_bf16 v[60:63], v[28:31], v[16:19], v[68:71]
	v_mfma_f32_16x16x32_bf16 v[114:117], v[212:215], v[24:27], v[60:63]
	v_mfma_f32_16x16x32_bf16 v[60:63], v[8:11], v[242:245], v[72:75]
	v_mfma_f32_16x16x32_bf16 v[106:109], v[20:23], v[246:249], v[60:63]
	v_mfma_f32_16x16x32_bf16 v[60:63], v[28:31], v[242:245], v[76:79]
	v_mfma_f32_16x16x32_bf16 v[98:101], v[212:215], v[246:249], v[60:63]
	v_mfma_f32_16x16x32_bf16 v[60:63], v[8:11], v[228:231], v[80:83]
	v_mfma_f32_16x16x32_bf16 v[88:91], v[20:23], v[180:183], v[60:63]
	v_mfma_f32_16x16x32_bf16 v[60:63], v[28:31], v[228:231], v[84:87]
	v_mfma_f32_16x16x32_bf16 v[80:83], v[212:215], v[180:183], v[60:63]
	v_mfma_f32_16x16x32_bf16 v[60:63], v[8:11], v[184:187], v[92:95]
	v_mfma_f32_16x16x32_bf16 v[72:75], v[20:23], v[224:227], v[60:63]
	v_mfma_f32_16x16x32_bf16 v[60:63], v[28:31], v[184:187], v[102:105]
	v_mfma_f32_16x16x32_bf16 v[60:63], v[212:215], v[224:227], v[60:63]
	s_setprio 0
	s_setprio 1
	v_mfma_f32_16x16x32_bf16 v[64:67], v[216:219], v[16:19], v[110:113]
	v_mfma_f32_16x16x32_bf16 v[16:19], v[234:237], v[16:19], v[32:35]
	v_mfma_f32_16x16x32_bf16 v[118:121], v[238:241], v[24:27], v[16:19]
	v_mfma_f32_16x16x32_bf16 v[16:19], v[216:219], v[242:245], v[36:39]
	v_mfma_f32_16x16x32_bf16 v[110:113], v[220:223], v[246:249], v[16:19]
	v_mfma_f32_16x16x32_bf16 v[16:19], v[234:237], v[242:245], v[40:43]
	v_mfma_f32_16x16x32_bf16 v[102:105], v[238:241], v[246:249], v[16:19]
	v_mfma_f32_16x16x32_bf16 v[16:19], v[216:219], v[228:231], v[44:47]
	v_mfma_f32_16x16x32_bf16 v[92:95], v[220:223], v[180:183], v[16:19]
	v_mfma_f32_16x16x32_bf16 v[16:19], v[234:237], v[228:231], v[48:51]
	v_mfma_f32_16x16x32_bf16 v[84:87], v[238:241], v[180:183], v[16:19]
	v_mfma_f32_16x16x32_bf16 v[16:19], v[216:219], v[184:187], v[52:55]
	v_mfma_f32_16x16x32_bf16 v[76:79], v[220:223], v[224:227], v[16:19]
	v_mfma_f32_16x16x32_bf16 v[16:19], v[234:237], v[184:187], v[56:59]
	v_mfma_f32_16x16x32_bf16 v[126:129], v[220:223], v[24:27], v[64:67]
	v_mfma_f32_16x16x32_bf16 v[68:71], v[238:241], v[224:227], v[16:19]
	s_setprio 0
	s_barrier
; template <class Epi, class Sched, bool ALIGN_EPI = false, bool SP2 = false>
; __device__ __forceinline__ void gemm_phase(PG8_LAS unsigned char* lds, const Gemm g, const Sched& S, const Epi& E) {
;     ...
;         if constexpr (Epi::PEEL) {
;             const char* a1 = cA + kstepA; const char* a2 = cA + 2 * kstepA; const char* b2 = cB + 2 * kstepB; const char* a3 = a2 + kstepA; const char* b3 = b2 + kstepB;
;             PG8_ITER(8);
;         }
	s_mov_b64 s[2:3], 0x180
	s_add_i32 s99, s99, s9
	s_nop 1
	v_lshl_add_u64 v[16:17], v[154:155], 0, s[2:3]
	s_mov_b32 m0, s99
	s_add_i32 vcc_lo, s99, 0x2000
	ds_read_b128 v[36:39], v156 offset:49152
	ds_read_b128 v[44:47], v156 offset:50176
	ds_read_b128 v[180:183], v156 offset:51200
	ds_read_b128 v[184:187], v156 offset:52224
	ds_read_b128 v[224:227], v156 offset:53248
	ds_read_b128 v[228:231], v156 offset:54272
	ds_read_b128 v[242:245], v156 offset:55296
	ds_read_b128 v[246:249], v156 offset:56320
	global_load_lds_dwordx4 v[16:17], off
	v_lshl_add_u64 v[16:17], v[178:179], 0, s[2:3]
	s_add_u32 s2, s0, 0x40180
	s_mov_b32 m0, vcc_lo
	s_addc_u32 s3, s1, 0
	s_add_i32 vcc_hi, vcc_hi, s9
	global_load_lds_dwordx4 v[16:17], off
	s_mov_b32 m0, vcc_hi
	s_add_i32 s38, vcc_hi, 0x2000
	global_load_lds_dwordx4 v132, s[2:3]
	s_mov_b32 m0, s38
	s_nop 0
	global_load_lds_dwordx4 v136, s[2:3]
	s_mov_b32 m0, s49
	s_nop 0
	global_load_lds_dwordx4 v130, s[42:43]
	s_mov_b32 m0, s50
	s_nop 0
	global_load_lds_dwordx4 v134, s[42:43]
	s_waitcnt vmcnt(8)
	s_waitcnt lgkmcnt(0)
	s_barrier
	s_setprio 1
	s_waitcnt lgkmcnt(0)
	v_mfma_f32_16x16x32_bf16 v[16:19], v[8:11], v[36:39], v[146:149]
	v_mfma_f32_16x16x32_bf16 v[56:59], v[20:23], v[44:47], v[16:19]
	v_mfma_f32_16x16x32_bf16 v[16:19], v[28:31], v[36:39], v[150:153]
	v_mfma_f32_16x16x32_bf16 v[48:51], v[212:215], v[44:47], v[16:19]
	v_mfma_f32_16x16x32_bf16 v[16:19], v[8:11], v[180:183], v[158:161]
	v_mfma_f32_16x16x32_bf16 v[40:43], v[20:23], v[184:187], v[16:19]
	v_mfma_f32_16x16x32_bf16 v[16:19], v[28:31], v[180:183], v[162:165]
	v_mfma_f32_16x16x32_bf16 v[32:35], v[212:215], v[184:187], v[16:19]
	v_mfma_f32_16x16x32_bf16 v[16:19], v[8:11], v[224:227], v[166:169]
	v_mfma_f32_16x16x32_bf16 v[0:3], v[8:11], v[242:245], v[0:3]
	v_mfma_f32_16x16x32_bf16 v[24:27], v[20:23], v[228:231], v[16:19]
	v_mfma_f32_16x16x32_bf16 v[16:19], v[28:31], v[224:227], v[170:173]
	v_mfma_f32_16x16x32_bf16 v[8:11], v[20:23], v[246:249], v[0:3]
	v_mfma_f32_16x16x32_bf16 v[0:3], v[28:31], v[242:245], v[4:7]
	v_mfma_f32_16x16x32_bf16 v[16:19], v[212:215], v[228:231], v[16:19]
	v_mfma_f32_16x16x32_bf16 v[0:3], v[212:215], v[246:249], v[0:3]
	s_setprio 0
	s_setprio 1
	v_mfma_f32_16x16x32_bf16 v[4:7], v[216:219], v[36:39], v[12:15]
	v_mfma_f32_16x16x32_bf16 v[64:67], v[220:223], v[44:47], v[4:7]
	v_mfma_f32_16x16x32_bf16 v[4:7], v[234:237], v[36:39], v[174:177]
	v_mfma_f32_16x16x32_bf16 v[52:55], v[238:241], v[44:47], v[4:7]
	v_mfma_f32_16x16x32_bf16 v[4:7], v[216:219], v[180:183], v[188:191]
	v_mfma_f32_16x16x32_bf16 v[44:47], v[220:223], v[184:187], v[4:7]
	v_mfma_f32_16x16x32_bf16 v[4:7], v[234:237], v[180:183], v[192:195]
	v_mfma_f32_16x16x32_bf16 v[36:39], v[238:241], v[184:187], v[4:7]
	v_mfma_f32_16x16x32_bf16 v[4:7], v[216:219], v[224:227], v[196:199]
	v_mfma_f32_16x16x32_bf16 v[28:31], v[220:223], v[228:231], v[4:7]
	v_mfma_f32_16x16x32_bf16 v[4:7], v[234:237], v[224:227], v[200:203]
	v_mfma_f32_16x16x32_bf16 v[20:23], v[238:241], v[228:231], v[4:7]
	v_mfma_f32_16x16x32_bf16 v[4:7], v[216:219], v[242:245], v[204:207]
	v_mfma_f32_16x16x32_bf16 v[12:15], v[220:223], v[246:249], v[4:7]
	v_mfma_f32_16x16x32_bf16 v[4:7], v[234:237], v[242:245], v[208:211]
	v_mfma_f32_16x16x32_bf16 v[4:7], v[238:241], v[246:249], v[4:7]
	s_setprio 0
	s_barrier
	s_add_u32 s3, s0, 0x200
	s_addc_u32 s2, s1, 0
	s_add_u32 s0, s34, 0xc04000
	s_addc_u32 s1, s35, 0
	s_mov_b32 s18, 0
